# version 93 plus in-proj loop: B fragment tuple v[144:147] moved to v[246:249] so that MFMA srcA/srcB tuples share the same bank alignment class
# baseline (speedup 1.0000x reference)
; #define PG8_STAGE(bufoff, gbase, voff) do { _Pragma("unroll") for (int _i = 0; _i < 2; ++_i) \
;         __builtin_amdgcn_global_load_lds((const unsigned*)((const char*)(gbase) + (voff)[_i]), (PG8_LAS unsigned*)(lds + (bufoff) + ldsw + _i * 8192), 16, 0, 0); } while (0)
; #define PG8_LDA(dst, b, h) do { _Pragma("unroll") for (int m = 0; m < 4; ++m) _Pragma("unroll") for (int k = 0; k < 2; ++k) dst[m][k] = *(const PG8_LAS bf16x8*)(lds + PG8_SA(b, h) + aoff + m * 2048 + k * 1024); } while (0)
; #define PG8_LDB(dst, b, h) do { _Pragma("unroll") for (int n = 0; n < 2; ++n) _Pragma("unroll") for (int k = 0; k < 2; ++k) dst[n][k] = *(const PG8_LAS bf16x8*)(lds + PG8_SB(b, h) + boff + n * 2048 + k * 1024); } while (0)
; #define PG8_MMA(ai, bj, At, Bt) do { __builtin_amdgcn_s_setprio(1); _Pragma("unroll") for (int m = 0; m < 4; ++m) _Pragma("unroll") for (int n = 0; n < 2; ++n) _Pragma("unroll") for (int k = 0; k < 2; ++k) \
;         acc[ai][bj][m][n] = __builtin_amdgcn_mfma_f32_16x16x32_bf16(Bt[n][k], At[m][k], acc[ai][bj][m][n], 0, 0, 0); __builtin_amdgcn_s_setprio(0); } while (0)
; template <class Epi, class Sched, bool ALIGN_EPI = false, bool SP2 = false>
; __device__ __forceinline__ void gemm_phase(PG8_LAS unsigned char* lds, const Gemm g, const Sched& S, const Epi& E, const int tid_in) {
;     ...
;         const bool has_next = S.next(ui + 1, nxt);
;         const char* nA = has_next ? (const char*)g.A + (size_t)nxt.pm * tstep : cA; const char* nB = has_next ? (const char*)g.Bt + (size_t)nxt.pn * tstep : cB;
;         for (int t = 0; t < nt; t += 2) {
;             const bool last = (t == nt - 2);
;             const char* a1 = cA + (size_t)(t + 1) * kstep;
;             const char* a2 = last ? nA : cA + (size_t)(t + 2) * kstep; const char* b2 = last ? nB : cB + (size_t)(t + 2) * kstep;
;             const char* a3 = a2 + kstep; const char* b3 = b2 + kstep;
;             if (last && has_next) S.a_ready(nxt);
;             if constexpr (SP2) {
;             PG8_LDB(B0, 0, 0); PG8_LDB(B1, 0, 1); PG8_SCHED; PG8_LDA(At, 0, 0); PG8_STAGE(PG8_SA(1, 1), a1 + hstep, voffA);
;             PG8_WAIT_V(8); PG8_WAIT_L(0); PG8_BAR; PG8_MMA(0, 0, At, B0); PG8_MMA(0, 1, At, B1); PG8_BAR; PG8_SCHED;
;             PG8_LDA(At, 0, 1); PG8_STAGE(PG8_SB(0, 0), b2, voffB); PG8_STAGE(PG8_SB(0, 1), b2 + hstep, voffB); PG8_STAGE(PG8_SA(0, 0), a2, voffA);
.LBB0_92:
	s_ashr_i32 s25, s24, 31
	s_lshl_b64 s[16:17], s[24:25], 19
	s_add_u32 s34, s84, s16
	s_addc_u32 s35, s85, s17
	s_and_b64 s[16:17], s[36:37], exec
	s_cselect_b32 s11, s35, s15
	s_cselect_b32 s16, s34, s14
	s_ashr_i32 s21, s20, 31
	s_lshl_b64 s[40:41], s[20:21], 19
	s_add_u32 s40, s3, s40
	s_addc_u32 s41, s18, s41
	s_and_b64 s[42:43], s[36:37], exec
	s_cselect_b32 s17, s41, s13
	s_cselect_b32 s21, s40, s12
	s_add_u32 s42, s14, 0x40080
	s_addc_u32 s43, s15, 0
	s_add_u32 s25, s12, 0x100
	s_addc_u32 s39, s13, 0
	s_mov_b32 s45, -2
	s_add_u32 s12, s42, 0xfffc0080
	s_addc_u32 s13, s43, -1
	s_add_i32 s46, 0, 0x10000
	s_cmp_eq_u32 s45, 12
	s_cselect_b32 s15, s11, s13
	s_cselect_b32 s14, s16, s12
	v_add_u32_e32 v148, s46, v150
	s_cselect_b32 s13, s17, s39
	s_cselect_b32 s12, s21, s25
	s_add_i32 s48, 0, 0x14000
	ds_read_b128 v[246:249], v148
	ds_read_b128 v[154:157], v148 offset:1024
	ds_read_b128 v[158:161], v148 offset:2048
	ds_read_b128 v[162:165], v148 offset:3072
	v_add_u32_e32 v148, s48, v150
	ds_read_b128 v[166:169], v148
	ds_read_b128 v[170:173], v148 offset:1024
	ds_read_b128 v[174:177], v148 offset:2048
	ds_read_b128 v[178:181], v148 offset:3072
	v_lshl_add_u64 v[148:149], s[42:43], 0, v[140:141]
	s_add_i32 m0, s22, 0xc000
	ds_read_b128 v[182:185], v152
	ds_read_b128 v[186:189], v152 offset:1024
	ds_read_b128 v[190:193], v152 offset:2048
	ds_read_b128 v[198:201], v152 offset:3072
	ds_read_b128 v[202:205], v152 offset:4096
	ds_read_b128 v[206:209], v152 offset:5120
	ds_read_b128 v[210:213], v152 offset:6144
	ds_read_b128 v[214:217], v152 offset:7168
	global_load_lds_dwordx4 v[148:149], off
	v_lshl_add_u64 v[148:149], s[42:43], 0, v[142:143]
	s_add_i32 m0, s22, 0xe000
	s_nop 0
	global_load_lds_dwordx4 v[148:149], off
	s_nop 0
	s_waitcnt vmcnt(8)
	s_waitcnt lgkmcnt(0)
	s_barrier
	v_mfma_f32_16x16x32_bf16 v[130:133], v[246:249], v[182:185], 0
	v_mfma_f32_16x16x32_bf16 v[130:133], v[154:157], v[186:189], v[130:133]
	v_mfma_f32_16x16x32_bf16 v[114:117], v[246:249], v[190:193], 0
	v_mfma_f32_16x16x32_bf16 v[114:117], v[154:157], v[198:201], v[114:117]
	v_mfma_f32_16x16x32_bf16 v[98:101], v[246:249], v[202:205], 0
	v_mfma_f32_16x16x32_bf16 v[98:101], v[154:157], v[206:209], v[98:101]
	v_mfma_f32_16x16x32_bf16 v[82:85], v[246:249], v[210:213], 0
	v_mfma_f32_16x16x32_bf16 v[82:85], v[154:157], v[214:217], v[82:85]
	v_mfma_f32_16x16x32_bf16 v[126:129], v[158:161], v[182:185], 0
	v_mfma_f32_16x16x32_bf16 v[126:129], v[162:165], v[186:189], v[126:129]
	v_mfma_f32_16x16x32_bf16 v[110:113], v[158:161], v[190:193], 0
	v_mfma_f32_16x16x32_bf16 v[110:113], v[162:165], v[198:201], v[110:113]
	v_mfma_f32_16x16x32_bf16 v[94:97], v[158:161], v[202:205], 0
	v_mfma_f32_16x16x32_bf16 v[94:97], v[162:165], v[206:209], v[94:97]
	v_mfma_f32_16x16x32_bf16 v[78:81], v[158:161], v[210:213], 0
	v_mfma_f32_16x16x32_bf16 v[78:81], v[162:165], v[214:217], v[78:81]
	v_mfma_f32_16x16x32_bf16 v[122:125], v[166:169], v[182:185], 0
	v_mfma_f32_16x16x32_bf16 v[122:125], v[170:173], v[186:189], v[122:125]
	v_mfma_f32_16x16x32_bf16 v[106:109], v[166:169], v[190:193], 0
	v_mfma_f32_16x16x32_bf16 v[106:109], v[170:173], v[198:201], v[106:109]
	v_mfma_f32_16x16x32_bf16 v[90:93], v[166:169], v[202:205], 0
	v_mfma_f32_16x16x32_bf16 v[90:93], v[170:173], v[206:209], v[90:93]
	v_mfma_f32_16x16x32_bf16 v[74:77], v[166:169], v[210:213], 0
	v_mfma_f32_16x16x32_bf16 v[74:77], v[170:173], v[214:217], v[74:77]
	v_mfma_f32_16x16x32_bf16 v[118:121], v[174:177], v[182:185], 0
	v_mfma_f32_16x16x32_bf16 v[118:121], v[178:181], v[186:189], v[118:121]
	v_mfma_f32_16x16x32_bf16 v[102:105], v[174:177], v[190:193], 0
	v_mfma_f32_16x16x32_bf16 v[102:105], v[178:181], v[198:201], v[102:105]
	v_mfma_f32_16x16x32_bf16 v[86:89], v[174:177], v[202:205], 0
	v_mfma_f32_16x16x32_bf16 v[86:89], v[178:181], v[206:209], v[86:89]
	v_mfma_f32_16x16x32_bf16 v[70:73], v[174:177], v[210:213], 0
	v_mfma_f32_16x16x32_bf16 v[70:73], v[178:181], v[214:217], v[70:73]
	s_barrier
	s_add_i32 s46, s46, s19
	v_lshl_add_u64 v[148:149], s[12:13], 0, v[134:135]
	s_mov_b32 m0, s46
	ds_read_b128 v[182:185], v152 offset:16384
	ds_read_b128 v[186:189], v152 offset:17408
	ds_read_b128 v[190:193], v152 offset:18432
	ds_read_b128 v[198:201], v152 offset:19456
	ds_read_b128 v[202:205], v152 offset:20480
	ds_read_b128 v[206:209], v152 offset:21504
	ds_read_b128 v[210:213], v152 offset:22528
	ds_read_b128 v[214:217], v152 offset:23552
	global_load_lds_dwordx4 v[148:149], off
	s_add_i32 m0, s46, 0x2000
	s_add_u32 s46, s12, 0x40000
	v_lshl_add_u64 v[218:219], s[12:13], 0, v[138:139]
	s_addc_u32 s47, s13, 0
	s_add_i32 s48, s48, s19
	global_load_lds_dwordx4 v[218:219], off
	v_lshl_add_u64 v[220:221], s[46:47], 0, v[134:135]
	s_mov_b32 m0, s48
	v_lshl_add_u64 v[222:223], s[14:15], 0, v[136:137]
	global_load_lds_dwordx4 v[220:221], off
	v_lshl_add_u64 v[220:221], s[46:47], 0, v[138:139]
	s_add_i32 m0, s48, 0x2000
	s_nop 0
	global_load_lds_dwordx4 v[220:221], off
	v_lshl_add_u64 v[220:221], s[14:15], 0, v[2:3]
	s_mov_b32 m0, s22
	s_nop 0
	global_load_lds_dwordx4 v[220:221], off
	s_mov_b32 m0, s23
	s_nop 0
	global_load_lds_dwordx4 v[222:223], off
	s_waitcnt vmcnt(8)
	s_waitcnt lgkmcnt(0)
	s_barrier
; #define PG8_STAGE(bufoff, gbase, voff) do { _Pragma("unroll") for (int _i = 0; _i < 2; ++_i) \
;         __builtin_amdgcn_global_load_lds((const unsigned*)((const char*)(gbase) + (voff)[_i]), (PG8_LAS unsigned*)(lds + (bufoff) + ldsw + _i * 8192), 16, 0, 0); } while (0)
; #define PG8_LDA(dst, b, h) do { _Pragma("unroll") for (int m = 0; m < 4; ++m) _Pragma("unroll") for (int k = 0; k < 2; ++k) dst[m][k] = *(const PG8_LAS bf16x8*)(lds + PG8_SA(b, h) + aoff + m * 2048 + k * 1024); } while (0)
; #define PG8_LDB(dst, b, h) do { _Pragma("unroll") for (int n = 0; n < 2; ++n) _Pragma("unroll") for (int k = 0; k < 2; ++k) dst[n][k] = *(const PG8_LAS bf16x8*)(lds + PG8_SB(b, h) + boff + n * 2048 + k * 1024); } while (0)
; #define PG8_MMA(ai, bj, At, Bt) do { __builtin_amdgcn_s_setprio(1); _Pragma("unroll") for (int m = 0; m < 4; ++m) _Pragma("unroll") for (int n = 0; n < 2; ++n) _Pragma("unroll") for (int k = 0; k < 2; ++k) \
;         acc[ai][bj][m][n] = __builtin_amdgcn_mfma_f32_16x16x32_bf16(Bt[n][k], At[m][k], acc[ai][bj][m][n], 0, 0, 0); __builtin_amdgcn_s_setprio(0); } while (0)
; #define PG8_WAIT_V(n) asm volatile("s_waitcnt vmcnt(" #n ")" ::: "memory")
; #define PG8_WAIT_L(n) asm volatile("s_waitcnt lgkmcnt(" #n ")" ::: "memory")
; #define PG8_BAR __builtin_amdgcn_s_barrier()
; #define PG8_SCHED __builtin_amdgcn_sched_barrier(0)
; template <class Epi, class Sched, bool ALIGN_EPI = false, bool SP2 = false>
; __device__ __forceinline__ void gemm_phase(PG8_LAS unsigned char* lds, const Gemm g, const Sched& S, const Epi& E, const int tid_in) {
;     ...
;             PG8_WAIT_V(8); PG8_WAIT_L(0); PG8_BAR; PG8_MMA(1, 0, At, B0); PG8_MMA(1, 1, At, B1); PG8_BAR; PG8_SCHED;
;             PG8_LDB(B0, 1, 0); PG8_LDB(B1, 1, 1); PG8_SCHED; PG8_LDA(At, 1, 0); PG8_STAGE(PG8_SA(0, 1), a2 + hstep, voffA);
;             PG8_WAIT_V(8); PG8_WAIT_L(0); PG8_BAR; PG8_MMA(0, 0, At, B0); PG8_MMA(0, 1, At, B1); PG8_BAR; PG8_SCHED;
	v_mfma_f32_16x16x32_bf16 v[66:69], v[246:249], v[182:185], 0
	v_mfma_f32_16x16x32_bf16 v[66:69], v[154:157], v[186:189], v[66:69]
	v_mfma_f32_16x16x32_bf16 v[50:53], v[246:249], v[190:193], 0
	v_mfma_f32_16x16x32_bf16 v[50:53], v[154:157], v[198:201], v[50:53]
	v_mfma_f32_16x16x32_bf16 v[34:37], v[246:249], v[202:205], 0
	v_mfma_f32_16x16x32_bf16 v[34:37], v[154:157], v[206:209], v[34:37]
	v_mfma_f32_16x16x32_bf16 v[18:21], v[246:249], v[210:213], 0
	v_mfma_f32_16x16x32_bf16 v[18:21], v[154:157], v[214:217], v[18:21]
	v_mfma_f32_16x16x32_bf16 v[62:65], v[158:161], v[182:185], 0
	v_mfma_f32_16x16x32_bf16 v[62:65], v[162:165], v[186:189], v[62:65]
	v_mfma_f32_16x16x32_bf16 v[46:49], v[158:161], v[190:193], 0
	v_mfma_f32_16x16x32_bf16 v[46:49], v[162:165], v[198:201], v[46:49]
	v_mfma_f32_16x16x32_bf16 v[30:33], v[158:161], v[202:205], 0
	v_mfma_f32_16x16x32_bf16 v[30:33], v[162:165], v[206:209], v[30:33]
	v_mfma_f32_16x16x32_bf16 v[14:17], v[158:161], v[210:213], 0
	v_mfma_f32_16x16x32_bf16 v[14:17], v[162:165], v[214:217], v[14:17]
	v_mfma_f32_16x16x32_bf16 v[58:61], v[166:169], v[182:185], 0
	v_mfma_f32_16x16x32_bf16 v[58:61], v[170:173], v[186:189], v[58:61]
	v_mfma_f32_16x16x32_bf16 v[42:45], v[166:169], v[190:193], 0
	v_mfma_f32_16x16x32_bf16 v[42:45], v[170:173], v[198:201], v[42:45]
	v_mfma_f32_16x16x32_bf16 v[26:29], v[166:169], v[202:205], 0
	v_mfma_f32_16x16x32_bf16 v[26:29], v[170:173], v[206:209], v[26:29]
	v_mfma_f32_16x16x32_bf16 v[10:13], v[166:169], v[210:213], 0
	v_mfma_f32_16x16x32_bf16 v[10:13], v[170:173], v[214:217], v[10:13]
	v_mfma_f32_16x16x32_bf16 v[54:57], v[174:177], v[182:185], 0
	v_mfma_f32_16x16x32_bf16 v[54:57], v[178:181], v[186:189], v[54:57]
	v_mfma_f32_16x16x32_bf16 v[38:41], v[174:177], v[190:193], 0
	v_mfma_f32_16x16x32_bf16 v[38:41], v[178:181], v[198:201], v[38:41]
	v_mfma_f32_16x16x32_bf16 v[22:25], v[174:177], v[202:205], 0
	v_mfma_f32_16x16x32_bf16 v[22:25], v[178:181], v[206:209], v[22:25]
	v_mfma_f32_16x16x32_bf16 v[6:9], v[174:177], v[210:213], 0
	v_mfma_f32_16x16x32_bf16 v[6:9], v[178:181], v[214:217], v[6:9]
	s_barrier
	s_add_i32 s46, 0, 0x18000
	v_add_u32_e32 v153, s46, v150
	s_add_i32 s47, 0, 0x1c000
	ds_read_b128 v[246:249], v153
	ds_read_b128 v[154:157], v153 offset:1024
	ds_read_b128 v[158:161], v153 offset:2048
	ds_read_b128 v[162:165], v153 offset:3072
	v_add_u32_e32 v153, s47, v150
	ds_read_b128 v[166:169], v153
	ds_read_b128 v[170:173], v153 offset:1024
	ds_read_b128 v[174:177], v153 offset:2048
	ds_read_b128 v[178:181], v153 offset:3072
	s_add_u32 s14, s14, 0x40000
	s_addc_u32 s15, s15, 0
	s_mov_b32 m0, s26
	v_lshl_add_u64 v[224:225], s[14:15], 0, v[2:3]
	ds_read_b128 v[182:185], v152 offset:32768
	ds_read_b128 v[186:189], v152 offset:33792
	ds_read_b128 v[190:193], v152 offset:34816
	ds_read_b128 v[198:201], v152 offset:35840
	ds_read_b128 v[202:205], v152 offset:36864
	ds_read_b128 v[206:209], v152 offset:37888
	ds_read_b128 v[210:213], v152 offset:38912
	ds_read_b128 v[214:217], v152 offset:39936
	global_load_lds_dwordx4 v[224:225], off
	v_lshl_add_u64 v[224:225], s[14:15], 0, v[136:137]
	s_mov_b32 m0, s27
	s_nop 0
	global_load_lds_dwordx4 v[224:225], off
	s_waitcnt vmcnt(8)
	s_waitcnt lgkmcnt(0)
	s_barrier
	v_mfma_f32_16x16x32_bf16 v[130:133], v[246:249], v[182:185], v[130:133]
	v_mfma_f32_16x16x32_bf16 v[130:133], v[154:157], v[186:189], v[130:133]
	v_mfma_f32_16x16x32_bf16 v[114:117], v[246:249], v[190:193], v[114:117]
	v_mfma_f32_16x16x32_bf16 v[114:117], v[154:157], v[198:201], v[114:117]
	v_mfma_f32_16x16x32_bf16 v[98:101], v[246:249], v[202:205], v[98:101]
	v_mfma_f32_16x16x32_bf16 v[98:101], v[154:157], v[206:209], v[98:101]
	v_mfma_f32_16x16x32_bf16 v[82:85], v[246:249], v[210:213], v[82:85]
	v_mfma_f32_16x16x32_bf16 v[82:85], v[154:157], v[214:217], v[82:85]
	v_mfma_f32_16x16x32_bf16 v[126:129], v[158:161], v[182:185], v[126:129]
	v_mfma_f32_16x16x32_bf16 v[126:129], v[162:165], v[186:189], v[126:129]
	v_mfma_f32_16x16x32_bf16 v[110:113], v[158:161], v[190:193], v[110:113]
	v_mfma_f32_16x16x32_bf16 v[110:113], v[162:165], v[198:201], v[110:113]
	v_mfma_f32_16x16x32_bf16 v[94:97], v[158:161], v[202:205], v[94:97]
	v_mfma_f32_16x16x32_bf16 v[94:97], v[162:165], v[206:209], v[94:97]
	v_mfma_f32_16x16x32_bf16 v[78:81], v[158:161], v[210:213], v[78:81]
	v_mfma_f32_16x16x32_bf16 v[78:81], v[162:165], v[214:217], v[78:81]
	v_mfma_f32_16x16x32_bf16 v[122:125], v[166:169], v[182:185], v[122:125]
	v_mfma_f32_16x16x32_bf16 v[122:125], v[170:173], v[186:189], v[122:125]
	v_mfma_f32_16x16x32_bf16 v[106:109], v[166:169], v[190:193], v[106:109]
	v_mfma_f32_16x16x32_bf16 v[106:109], v[170:173], v[198:201], v[106:109]
	v_mfma_f32_16x16x32_bf16 v[90:93], v[166:169], v[202:205], v[90:93]
	v_mfma_f32_16x16x32_bf16 v[90:93], v[170:173], v[206:209], v[90:93]
	v_mfma_f32_16x16x32_bf16 v[74:77], v[166:169], v[210:213], v[74:77]
	v_mfma_f32_16x16x32_bf16 v[74:77], v[170:173], v[214:217], v[74:77]
	v_mfma_f32_16x16x32_bf16 v[118:121], v[174:177], v[182:185], v[118:121]
	v_mfma_f32_16x16x32_bf16 v[118:121], v[178:181], v[186:189], v[118:121]
	v_mfma_f32_16x16x32_bf16 v[102:105], v[174:177], v[190:193], v[102:105]
	v_mfma_f32_16x16x32_bf16 v[102:105], v[178:181], v[198:201], v[102:105]
	v_mfma_f32_16x16x32_bf16 v[86:89], v[174:177], v[202:205], v[86:89]
	v_mfma_f32_16x16x32_bf16 v[86:89], v[178:181], v[206:209], v[86:89]
	v_mfma_f32_16x16x32_bf16 v[70:73], v[174:177], v[210:213], v[70:73]
	v_mfma_f32_16x16x32_bf16 v[70:73], v[178:181], v[214:217], v[70:73]
	s_barrier
; #define PG8_STAGE(bufoff, gbase, voff) do { _Pragma("unroll") for (int _i = 0; _i < 2; ++_i) \
;         __builtin_amdgcn_global_load_lds((const unsigned*)((const char*)(gbase) + (voff)[_i]), (PG8_LAS unsigned*)(lds + (bufoff) + ldsw + _i * 8192), 16, 0, 0); } while (0)
; #define PG8_LDA(dst, b, h) do { _Pragma("unroll") for (int m = 0; m < 4; ++m) _Pragma("unroll") for (int k = 0; k < 2; ++k) dst[m][k] = *(const PG8_LAS bf16x8*)(lds + PG8_SA(b, h) + aoff + m * 2048 + k * 1024); } while (0)
; #define PG8_LDB(dst, b, h) do { _Pragma("unroll") for (int n = 0; n < 2; ++n) _Pragma("unroll") for (int k = 0; k < 2; ++k) dst[n][k] = *(const PG8_LAS bf16x8*)(lds + PG8_SB(b, h) + boff + n * 2048 + k * 1024); } while (0)
; #define PG8_WAIT_V(n) asm volatile("s_waitcnt vmcnt(" #n ")" ::: "memory")
; template <class Epi, class Sched, bool ALIGN_EPI = false, bool SP2 = false>
; __device__ __forceinline__ void gemm_phase(PG8_LAS unsigned char* lds, const Gemm g, const Sched& S, const Epi& E, const int tid_in) {
;     ...
;             PG8_LDB(B0, 0, 0); PG8_LDB(B1, 0, 1); PG8_SCHED; PG8_LDA(At, 0, 0); PG8_STAGE(PG8_SA(1, 1), a1 + hstep, voffA);
;             PG8_WAIT_V(8); PG8_WAIT_L(0); PG8_BAR; PG8_MMA(0, 0, At, B0); PG8_MMA(0, 1, At, B1); PG8_BAR; PG8_SCHED;
;             PG8_LDA(At, 0, 1); PG8_STAGE(PG8_SB(0, 0), b2, voffB); PG8_STAGE(PG8_SB(0, 1), b2 + hstep, voffB); PG8_STAGE(PG8_SA(0, 0), a2, voffA);
;             PG8_WAIT_V(8); PG8_WAIT_L(0); PG8_BAR; PG8_MMA(1, 0, At, B0); PG8_MMA(1, 1, At, B1); PG8_BAR; PG8_SCHED;
;             PG8_LDB(B0, 1, 0); PG8_LDB(B1, 1, 1); PG8_SCHED; PG8_LDA(At, 1, 0); PG8_STAGE(PG8_SA(0, 1), a2 + hstep, voffA);
;             PG8_WAIT_V(8); PG8_WAIT_L(0); PG8_BAR; PG8_MMA(0, 0, At, B0); PG8_MMA(0, 1, At, B1); PG8_BAR; PG8_SCHED;
;             PG8_LDA(At, 1, 1); PG8_STAGE(PG8_SB(1, 0), b3, voffB); PG8_STAGE(PG8_SB(1, 1), b3 + hstep, voffB); PG8_STAGE(PG8_SA(1, 0), a3, voffA);
;             PG8_WAIT_V(8); PG8_WAIT_L(0); PG8_BAR; PG8_MMA(1, 0, At, B0); PG8_MMA(1, 1, At, B1); PG8_BAR; PG8_SCHED;
;     __device__ __forceinline__ void operator()(const f32x4 (&acc)[2][2][4][2], const Unit& u, int wr, int wc, int fr, int fq) const {
;     ...
;         float rs[2][4];
; #pragma unroll
;         for (int ai = 0; ai < 2; ++ai)
; #pragma unroll
;             for (int m = 0; m < 4; ++m) rs[ai][m] = rowss[row0 + ai * HALF + m * 16];
	s_add_i32 s14, s46, s19
	v_lshl_add_u64 v[148:149], v[148:149], 0, s[28:29]
	s_mov_b32 m0, s14
	ds_read_b128 v[182:185], v152 offset:49152
	ds_read_b128 v[186:189], v152 offset:50176
	ds_read_b128 v[190:193], v152 offset:51200
	ds_read_b128 v[198:201], v152 offset:52224
	ds_read_b128 v[202:205], v152 offset:53248
	ds_read_b128 v[206:209], v152 offset:54272
	ds_read_b128 v[210:213], v152 offset:55296
	ds_read_b128 v[214:217], v152 offset:56320
	global_load_lds_dwordx4 v[148:149], off
	s_add_i32 m0, s14, 0x2000
	s_add_u32 s12, s12, 0x40080
	v_lshl_add_u64 v[148:149], v[218:219], 0, s[28:29]
	s_addc_u32 s13, s13, 0
	s_add_i32 s14, s47, s19
	global_load_lds_dwordx4 v[148:149], off
	v_lshl_add_u64 v[148:149], s[12:13], 0, v[134:135]
	s_mov_b32 m0, s14
	s_nop 0
	global_load_lds_dwordx4 v[148:149], off
	v_lshl_add_u64 v[148:149], s[12:13], 0, v[138:139]
	s_add_i32 m0, s14, 0x2000
	s_nop 0
	global_load_lds_dwordx4 v[148:149], off
	v_lshl_add_u64 v[148:149], v[220:221], 0, s[28:29]
	s_mov_b32 m0, s30
	s_nop 0
	global_load_lds_dwordx4 v[148:149], off
	v_lshl_add_u64 v[148:149], v[222:223], 0, s[28:29]
	s_mov_b32 m0, s31
	s_nop 0
	global_load_lds_dwordx4 v[148:149], off
	s_waitcnt vmcnt(8)
	s_waitcnt lgkmcnt(0)
	s_cmp_lg_u32 s45, 12
	s_cbranch_scc1 .Lrs_in_skip_pin
	v_lshl_add_u32 v148, s38, 8, v5
	v_ashrrev_i32_e32 v149, 31, v148
	v_lshl_add_u64 v[148:149], v[148:149], 2, s[6:7]
	global_load_dword v226, v[148:149], off
	global_load_dword v227, v[148:149], off offset:64
	global_load_dword v228, v[148:149], off offset:128
	global_load_dword v229, v[148:149], off offset:192
	global_load_dword v238, v[148:149], off offset:512
	global_load_dword v239, v[148:149], off offset:576
	global_load_dword v240, v[148:149], off offset:640
	global_load_dword v241, v[148:149], off offset:704
.Lrs_in_skip_pin:
	s_barrier
	v_mfma_f32_16x16x32_bf16 v[66:69], v[246:249], v[182:185], v[66:69]
	v_mfma_f32_16x16x32_bf16 v[66:69], v[154:157], v[186:189], v[66:69]
	v_mfma_f32_16x16x32_bf16 v[50:53], v[246:249], v[190:193], v[50:53]
	v_mfma_f32_16x16x32_bf16 v[50:53], v[154:157], v[198:201], v[50:53]
	v_mfma_f32_16x16x32_bf16 v[34:37], v[246:249], v[202:205], v[34:37]
	v_mfma_f32_16x16x32_bf16 v[34:37], v[154:157], v[206:209], v[34:37]
	v_mfma_f32_16x16x32_bf16 v[18:21], v[246:249], v[210:213], v[18:21]
	v_mfma_f32_16x16x32_bf16 v[18:21], v[154:157], v[214:217], v[18:21]
	v_mfma_f32_16x16x32_bf16 v[62:65], v[158:161], v[182:185], v[62:65]
	v_mfma_f32_16x16x32_bf16 v[62:65], v[162:165], v[186:189], v[62:65]
	v_mfma_f32_16x16x32_bf16 v[46:49], v[158:161], v[190:193], v[46:49]
	v_mfma_f32_16x16x32_bf16 v[46:49], v[162:165], v[198:201], v[46:49]
	v_mfma_f32_16x16x32_bf16 v[30:33], v[158:161], v[202:205], v[30:33]
	v_mfma_f32_16x16x32_bf16 v[30:33], v[162:165], v[206:209], v[30:33]
	v_mfma_f32_16x16x32_bf16 v[14:17], v[158:161], v[210:213], v[14:17]
	v_mfma_f32_16x16x32_bf16 v[14:17], v[162:165], v[214:217], v[14:17]
	v_mfma_f32_16x16x32_bf16 v[58:61], v[166:169], v[182:185], v[58:61]
	v_mfma_f32_16x16x32_bf16 v[58:61], v[170:173], v[186:189], v[58:61]
	v_mfma_f32_16x16x32_bf16 v[42:45], v[166:169], v[190:193], v[42:45]
	v_mfma_f32_16x16x32_bf16 v[42:45], v[170:173], v[198:201], v[42:45]
	v_mfma_f32_16x16x32_bf16 v[26:29], v[166:169], v[202:205], v[26:29]
	v_mfma_f32_16x16x32_bf16 v[26:29], v[170:173], v[206:209], v[26:29]
	v_mfma_f32_16x16x32_bf16 v[10:13], v[166:169], v[210:213], v[10:13]
	v_mfma_f32_16x16x32_bf16 v[10:13], v[170:173], v[214:217], v[10:13]
	v_mfma_f32_16x16x32_bf16 v[54:57], v[174:177], v[182:185], v[54:57]
	v_mfma_f32_16x16x32_bf16 v[54:57], v[178:181], v[186:189], v[54:57]
	v_mfma_f32_16x16x32_bf16 v[38:41], v[174:177], v[190:193], v[38:41]
	v_mfma_f32_16x16x32_bf16 v[38:41], v[178:181], v[198:201], v[38:41]
	v_mfma_f32_16x16x32_bf16 v[22:25], v[174:177], v[202:205], v[22:25]
	v_mfma_f32_16x16x32_bf16 v[22:25], v[178:181], v[206:209], v[22:25]
	v_mfma_f32_16x16x32_bf16 v[6:9], v[174:177], v[210:213], v[6:9]
	v_mfma_f32_16x16x32_bf16 v[6:9], v[178:181], v[214:217], v[6:9]
	s_barrier
	s_add_i32 s45, s45, 2
	s_add_u32 s42, s42, 0x100
	s_addc_u32 s43, s43, 0
	s_add_u32 s25, s25, 0x100
	s_addc_u32 s39, s39, 0
	s_cmp_gt_u32 s45, 13
.LBB0_93:
	s_add_u32 s12, s42, 0xfffc0080
	s_addc_u32 s13, s43, -1
	s_add_i32 s46, 0, 0x10000
	s_cmp_eq_u32 s45, 12
	s_cselect_b32 s15, s11, s13
	s_cselect_b32 s14, s16, s12
	v_add_u32_e32 v148, s46, v150
	s_cselect_b32 s13, s17, s39
	s_cselect_b32 s12, s21, s25
	s_add_i32 s48, 0, 0x14000
	ds_read_b128 v[246:249], v148
	ds_read_b128 v[154:157], v148 offset:1024
	ds_read_b128 v[158:161], v148 offset:2048
	ds_read_b128 v[162:165], v148 offset:3072
	v_add_u32_e32 v148, s48, v150
	ds_read_b128 v[166:169], v148
	ds_read_b128 v[170:173], v148 offset:1024
	ds_read_b128 v[174:177], v148 offset:2048
	ds_read_b128 v[178:181], v148 offset:3072
	v_lshl_add_u64 v[148:149], s[42:43], 0, v[140:141]
	s_add_i32 m0, s22, 0xc000
	ds_read_b128 v[182:185], v152
	ds_read_b128 v[186:189], v152 offset:1024
	ds_read_b128 v[190:193], v152 offset:2048
	ds_read_b128 v[198:201], v152 offset:3072
	ds_read_b128 v[202:205], v152 offset:4096
	ds_read_b128 v[206:209], v152 offset:5120
	ds_read_b128 v[210:213], v152 offset:6144
	ds_read_b128 v[214:217], v152 offset:7168
	global_load_lds_dwordx4 v[148:149], off
	v_lshl_add_u64 v[148:149], s[42:43], 0, v[142:143]
	s_add_i32 m0, s22, 0xe000
	s_nop 0
	global_load_lds_dwordx4 v[148:149], off
	s_nop 0
	s_waitcnt vmcnt(8)
	s_waitcnt lgkmcnt(0)
	s_barrier
; #define PG8_STAGE(bufoff, gbase, voff) do { _Pragma("unroll") for (int _i = 0; _i < 2; ++_i) \
;         __builtin_amdgcn_global_load_lds((const unsigned*)((const char*)(gbase) + (voff)[_i]), (PG8_LAS unsigned*)(lds + (bufoff) + ldsw + _i * 8192), 16, 0, 0); } while (0)
; #define PG8_LDA(dst, b, h) do { _Pragma("unroll") for (int m = 0; m < 4; ++m) _Pragma("unroll") for (int k = 0; k < 2; ++k) dst[m][k] = *(const PG8_LAS bf16x8*)(lds + PG8_SA(b, h) + aoff + m * 2048 + k * 1024); } while (0)
; #define PG8_LDB(dst, b, h) do { _Pragma("unroll") for (int n = 0; n < 2; ++n) _Pragma("unroll") for (int k = 0; k < 2; ++k) dst[n][k] = *(const PG8_LAS bf16x8*)(lds + PG8_SB(b, h) + boff + n * 2048 + k * 1024); } while (0)
; #define PG8_MMA(ai, bj, At, Bt) do { __builtin_amdgcn_s_setprio(1); _Pragma("unroll") for (int m = 0; m < 4; ++m) _Pragma("unroll") for (int n = 0; n < 2; ++n) _Pragma("unroll") for (int k = 0; k < 2; ++k) \
;         acc[ai][bj][m][n] = __builtin_amdgcn_mfma_f32_16x16x32_bf16(Bt[n][k], At[m][k], acc[ai][bj][m][n], 0, 0, 0); __builtin_amdgcn_s_setprio(0); } while (0)
; #define PG8_WAIT_V(n) asm volatile("s_waitcnt vmcnt(" #n ")" ::: "memory")
; #define PG8_WAIT_L(n) asm volatile("s_waitcnt lgkmcnt(" #n ")" ::: "memory")
; #define PG8_BAR __builtin_amdgcn_s_barrier()
; #define PG8_SCHED __builtin_amdgcn_sched_barrier(0)
; template <class Epi, class Sched, bool ALIGN_EPI = false, bool SP2 = false>
; __device__ __forceinline__ void gemm_phase(PG8_LAS unsigned char* lds, const Gemm g, const Sched& S, const Epi& E, const int tid_in) {
;     ...
;             PG8_WAIT_V(8); PG8_WAIT_L(0); PG8_BAR; PG8_MMA(0, 0, At, B0); PG8_MMA(0, 1, At, B1); PG8_BAR; PG8_SCHED;
;             PG8_LDA(At, 0, 1); PG8_STAGE(PG8_SB(0, 0), b2, voffB); PG8_STAGE(PG8_SB(0, 1), b2 + hstep, voffB); PG8_STAGE(PG8_SA(0, 0), a2, voffA);
;             PG8_WAIT_V(8); PG8_WAIT_L(0); PG8_BAR; PG8_MMA(1, 0, At, B0); PG8_MMA(1, 1, At, B1); PG8_BAR; PG8_SCHED;
;             PG8_LDB(B0, 1, 0); PG8_LDB(B1, 1, 1); PG8_SCHED; PG8_LDA(At, 1, 0); PG8_STAGE(PG8_SA(0, 1), a2 + hstep, voffA);
;             PG8_WAIT_V(8); PG8_WAIT_L(0); PG8_BAR; PG8_MMA(0, 0, At, B0); PG8_MMA(0, 1, At, B1); PG8_BAR; PG8_SCHED;
;             PG8_LDA(At, 1, 1); PG8_STAGE(PG8_SB(1, 0), b3, voffB); PG8_STAGE(PG8_SB(1, 1), b3 + hstep, voffB); PG8_STAGE(PG8_SA(1, 0), a3, voffA);
	v_mfma_f32_16x16x32_bf16 v[130:133], v[246:249], v[182:185], v[130:133]
	v_mfma_f32_16x16x32_bf16 v[130:133], v[154:157], v[186:189], v[130:133]
	v_mfma_f32_16x16x32_bf16 v[114:117], v[246:249], v[190:193], v[114:117]
	v_mfma_f32_16x16x32_bf16 v[114:117], v[154:157], v[198:201], v[114:117]
	v_mfma_f32_16x16x32_bf16 v[98:101], v[246:249], v[202:205], v[98:101]
	v_mfma_f32_16x16x32_bf16 v[98:101], v[154:157], v[206:209], v[98:101]
	v_mfma_f32_16x16x32_bf16 v[82:85], v[246:249], v[210:213], v[82:85]
	v_mfma_f32_16x16x32_bf16 v[82:85], v[154:157], v[214:217], v[82:85]
	v_mfma_f32_16x16x32_bf16 v[126:129], v[158:161], v[182:185], v[126:129]
	v_mfma_f32_16x16x32_bf16 v[126:129], v[162:165], v[186:189], v[126:129]
	v_mfma_f32_16x16x32_bf16 v[110:113], v[158:161], v[190:193], v[110:113]
	v_mfma_f32_16x16x32_bf16 v[110:113], v[162:165], v[198:201], v[110:113]
	v_mfma_f32_16x16x32_bf16 v[94:97], v[158:161], v[202:205], v[94:97]
	v_mfma_f32_16x16x32_bf16 v[94:97], v[162:165], v[206:209], v[94:97]
	v_mfma_f32_16x16x32_bf16 v[78:81], v[158:161], v[210:213], v[78:81]
	v_mfma_f32_16x16x32_bf16 v[78:81], v[162:165], v[214:217], v[78:81]
	v_mfma_f32_16x16x32_bf16 v[122:125], v[166:169], v[182:185], v[122:125]
	v_mfma_f32_16x16x32_bf16 v[122:125], v[170:173], v[186:189], v[122:125]
	v_mfma_f32_16x16x32_bf16 v[106:109], v[166:169], v[190:193], v[106:109]
	v_mfma_f32_16x16x32_bf16 v[106:109], v[170:173], v[198:201], v[106:109]
	v_mfma_f32_16x16x32_bf16 v[90:93], v[166:169], v[202:205], v[90:93]
	v_mfma_f32_16x16x32_bf16 v[90:93], v[170:173], v[206:209], v[90:93]
	v_mfma_f32_16x16x32_bf16 v[74:77], v[166:169], v[210:213], v[74:77]
	v_mfma_f32_16x16x32_bf16 v[74:77], v[170:173], v[214:217], v[74:77]
	v_mfma_f32_16x16x32_bf16 v[118:121], v[174:177], v[182:185], v[118:121]
	v_mfma_f32_16x16x32_bf16 v[118:121], v[178:181], v[186:189], v[118:121]
	v_mfma_f32_16x16x32_bf16 v[102:105], v[174:177], v[190:193], v[102:105]
	v_mfma_f32_16x16x32_bf16 v[102:105], v[178:181], v[198:201], v[102:105]
	v_mfma_f32_16x16x32_bf16 v[86:89], v[174:177], v[202:205], v[86:89]
	v_mfma_f32_16x16x32_bf16 v[86:89], v[178:181], v[206:209], v[86:89]
	v_mfma_f32_16x16x32_bf16 v[70:73], v[174:177], v[210:213], v[70:73]
	v_mfma_f32_16x16x32_bf16 v[70:73], v[178:181], v[214:217], v[70:73]
	s_barrier
	s_add_i32 s46, s46, s19
	v_lshl_add_u64 v[148:149], s[12:13], 0, v[134:135]
	s_mov_b32 m0, s46
	ds_read_b128 v[182:185], v152 offset:16384
	ds_read_b128 v[186:189], v152 offset:17408
	ds_read_b128 v[190:193], v152 offset:18432
	ds_read_b128 v[198:201], v152 offset:19456
	ds_read_b128 v[202:205], v152 offset:20480
	ds_read_b128 v[206:209], v152 offset:21504
	ds_read_b128 v[210:213], v152 offset:22528
	ds_read_b128 v[214:217], v152 offset:23552
	global_load_lds_dwordx4 v[148:149], off
	s_add_i32 m0, s46, 0x2000
	s_add_u32 s46, s12, 0x40000
	v_lshl_add_u64 v[218:219], s[12:13], 0, v[138:139]
	s_addc_u32 s47, s13, 0
	s_add_i32 s48, s48, s19
	global_load_lds_dwordx4 v[218:219], off
	v_lshl_add_u64 v[220:221], s[46:47], 0, v[134:135]
	s_mov_b32 m0, s48
	v_lshl_add_u64 v[222:223], s[14:15], 0, v[136:137]
	global_load_lds_dwordx4 v[220:221], off
	v_lshl_add_u64 v[220:221], s[46:47], 0, v[138:139]
	s_add_i32 m0, s48, 0x2000
	s_nop 0
	global_load_lds_dwordx4 v[220:221], off
	v_lshl_add_u64 v[220:221], s[14:15], 0, v[2:3]
	s_mov_b32 m0, s22
	s_nop 0
	global_load_lds_dwordx4 v[220:221], off
	s_mov_b32 m0, s23
	s_nop 0
	global_load_lds_dwordx4 v[222:223], off
	s_waitcnt vmcnt(8)
	s_waitcnt lgkmcnt(0)
	s_barrier
	v_mfma_f32_16x16x32_bf16 v[66:69], v[246:249], v[182:185], v[66:69]
	v_mfma_f32_16x16x32_bf16 v[66:69], v[154:157], v[186:189], v[66:69]
	v_mfma_f32_16x16x32_bf16 v[50:53], v[246:249], v[190:193], v[50:53]
	v_mfma_f32_16x16x32_bf16 v[50:53], v[154:157], v[198:201], v[50:53]
	v_mfma_f32_16x16x32_bf16 v[34:37], v[246:249], v[202:205], v[34:37]
	v_mfma_f32_16x16x32_bf16 v[34:37], v[154:157], v[206:209], v[34:37]
	v_mfma_f32_16x16x32_bf16 v[18:21], v[246:249], v[210:213], v[18:21]
	v_mfma_f32_16x16x32_bf16 v[18:21], v[154:157], v[214:217], v[18:21]
	v_mfma_f32_16x16x32_bf16 v[62:65], v[158:161], v[182:185], v[62:65]
	v_mfma_f32_16x16x32_bf16 v[62:65], v[162:165], v[186:189], v[62:65]
	v_mfma_f32_16x16x32_bf16 v[46:49], v[158:161], v[190:193], v[46:49]
	v_mfma_f32_16x16x32_bf16 v[46:49], v[162:165], v[198:201], v[46:49]
	v_mfma_f32_16x16x32_bf16 v[30:33], v[158:161], v[202:205], v[30:33]
	v_mfma_f32_16x16x32_bf16 v[30:33], v[162:165], v[206:209], v[30:33]
	v_mfma_f32_16x16x32_bf16 v[14:17], v[158:161], v[210:213], v[14:17]
	v_mfma_f32_16x16x32_bf16 v[14:17], v[162:165], v[214:217], v[14:17]
	v_mfma_f32_16x16x32_bf16 v[58:61], v[166:169], v[182:185], v[58:61]
	v_mfma_f32_16x16x32_bf16 v[58:61], v[170:173], v[186:189], v[58:61]
	v_mfma_f32_16x16x32_bf16 v[42:45], v[166:169], v[190:193], v[42:45]
	v_mfma_f32_16x16x32_bf16 v[42:45], v[170:173], v[198:201], v[42:45]
	v_mfma_f32_16x16x32_bf16 v[26:29], v[166:169], v[202:205], v[26:29]
	v_mfma_f32_16x16x32_bf16 v[26:29], v[170:173], v[206:209], v[26:29]
	v_mfma_f32_16x16x32_bf16 v[10:13], v[166:169], v[210:213], v[10:13]
	v_mfma_f32_16x16x32_bf16 v[10:13], v[170:173], v[214:217], v[10:13]
	v_mfma_f32_16x16x32_bf16 v[54:57], v[174:177], v[182:185], v[54:57]
	v_mfma_f32_16x16x32_bf16 v[54:57], v[178:181], v[186:189], v[54:57]
	v_mfma_f32_16x16x32_bf16 v[38:41], v[174:177], v[190:193], v[38:41]
	v_mfma_f32_16x16x32_bf16 v[38:41], v[178:181], v[198:201], v[38:41]
	v_mfma_f32_16x16x32_bf16 v[22:25], v[174:177], v[202:205], v[22:25]
	v_mfma_f32_16x16x32_bf16 v[22:25], v[178:181], v[206:209], v[22:25]
	v_mfma_f32_16x16x32_bf16 v[6:9], v[174:177], v[210:213], v[6:9]
	v_mfma_f32_16x16x32_bf16 v[6:9], v[178:181], v[214:217], v[6:9]
	s_barrier
; #define PG8_STAGE(bufoff, gbase, voff) do { _Pragma("unroll") for (int _i = 0; _i < 2; ++_i) \
;         __builtin_amdgcn_global_load_lds((const unsigned*)((const char*)(gbase) + (voff)[_i]), (PG8_LAS unsigned*)(lds + (bufoff) + ldsw + _i * 8192), 16, 0, 0); } while (0)
; #define PG8_LDA(dst, b, h) do { _Pragma("unroll") for (int m = 0; m < 4; ++m) _Pragma("unroll") for (int k = 0; k < 2; ++k) dst[m][k] = *(const PG8_LAS bf16x8*)(lds + PG8_SA(b, h) + aoff + m * 2048 + k * 1024); } while (0)
; #define PG8_LDB(dst, b, h) do { _Pragma("unroll") for (int n = 0; n < 2; ++n) _Pragma("unroll") for (int k = 0; k < 2; ++k) dst[n][k] = *(const PG8_LAS bf16x8*)(lds + PG8_SB(b, h) + boff + n * 2048 + k * 1024); } while (0)
; #define PG8_MMA(ai, bj, At, Bt) do { __builtin_amdgcn_s_setprio(1); _Pragma("unroll") for (int m = 0; m < 4; ++m) _Pragma("unroll") for (int n = 0; n < 2; ++n) _Pragma("unroll") for (int k = 0; k < 2; ++k) \
;         acc[ai][bj][m][n] = __builtin_amdgcn_mfma_f32_16x16x32_bf16(Bt[n][k], At[m][k], acc[ai][bj][m][n], 0, 0, 0); __builtin_amdgcn_s_setprio(0); } while (0)
; #define PG8_WAIT_V(n) asm volatile("s_waitcnt vmcnt(" #n ")" ::: "memory")
; #define PG8_WAIT_L(n) asm volatile("s_waitcnt lgkmcnt(" #n ")" ::: "memory")
; #define PG8_BAR __builtin_amdgcn_s_barrier()
; template <class Epi, class Sched, bool ALIGN_EPI = false, bool SP2 = false>
; __device__ __forceinline__ void gemm_phase(PG8_LAS unsigned char* lds, const Gemm g, const Sched& S, const Epi& E, const int tid_in) {
;     ...
;             PG8_LDB(B0, 1, 0); PG8_LDB(B1, 1, 1); PG8_SCHED; PG8_LDA(At, 1, 0); PG8_STAGE(PG8_SA(0, 1), a2 + hstep, voffA);
;             PG8_WAIT_V(8); PG8_WAIT_L(0); PG8_BAR; PG8_MMA(0, 0, At, B0); PG8_MMA(0, 1, At, B1); PG8_BAR; PG8_SCHED;
;             PG8_LDA(At, 1, 1); PG8_STAGE(PG8_SB(1, 0), b3, voffB); PG8_STAGE(PG8_SB(1, 1), b3 + hstep, voffB); PG8_STAGE(PG8_SA(1, 0), a3, voffA);
;             PG8_WAIT_V(8); PG8_WAIT_L(0); PG8_BAR; PG8_MMA(1, 0, At, B0); PG8_MMA(1, 1, At, B1); PG8_BAR; PG8_SCHED;
;     __device__ __forceinline__ void operator()(const f32x4 (&acc)[2][2][4][2], const Unit& u, int wr, int wc, int fr, int fq) const {
;     ...
;         float rs[2][4];
; #pragma unroll
;         for (int ai = 0; ai < 2; ++ai)
; #pragma unroll
;             for (int m = 0; m < 4; ++m) rs[ai][m] = rowss[row0 + ai * HALF + m * 16];
	s_add_i32 s46, 0, 0x18000
	v_add_u32_e32 v153, s46, v150
	s_add_i32 s47, 0, 0x1c000
	ds_read_b128 v[246:249], v153
	ds_read_b128 v[154:157], v153 offset:1024
	ds_read_b128 v[158:161], v153 offset:2048
	ds_read_b128 v[162:165], v153 offset:3072
	v_add_u32_e32 v153, s47, v150
	ds_read_b128 v[166:169], v153
	ds_read_b128 v[170:173], v153 offset:1024
	ds_read_b128 v[174:177], v153 offset:2048
	ds_read_b128 v[178:181], v153 offset:3072
	s_add_u32 s14, s14, 0x40000
	s_addc_u32 s15, s15, 0
	s_mov_b32 m0, s26
	v_lshl_add_u64 v[224:225], s[14:15], 0, v[2:3]
	ds_read_b128 v[182:185], v152 offset:32768
	ds_read_b128 v[186:189], v152 offset:33792
	ds_read_b128 v[190:193], v152 offset:34816
	ds_read_b128 v[198:201], v152 offset:35840
	ds_read_b128 v[202:205], v152 offset:36864
	ds_read_b128 v[206:209], v152 offset:37888
	ds_read_b128 v[210:213], v152 offset:38912
	ds_read_b128 v[214:217], v152 offset:39936
	global_load_lds_dwordx4 v[224:225], off
	v_lshl_add_u64 v[224:225], s[14:15], 0, v[136:137]
	s_mov_b32 m0, s27
	s_nop 0
	global_load_lds_dwordx4 v[224:225], off
	s_waitcnt vmcnt(8)
	s_waitcnt lgkmcnt(0)
	s_barrier
	v_mfma_f32_16x16x32_bf16 v[130:133], v[246:249], v[182:185], v[130:133]
	v_mfma_f32_16x16x32_bf16 v[130:133], v[154:157], v[186:189], v[130:133]
	v_mfma_f32_16x16x32_bf16 v[114:117], v[246:249], v[190:193], v[114:117]
	v_mfma_f32_16x16x32_bf16 v[114:117], v[154:157], v[198:201], v[114:117]
	v_mfma_f32_16x16x32_bf16 v[98:101], v[246:249], v[202:205], v[98:101]
	v_mfma_f32_16x16x32_bf16 v[98:101], v[154:157], v[206:209], v[98:101]
	v_mfma_f32_16x16x32_bf16 v[82:85], v[246:249], v[210:213], v[82:85]
	v_mfma_f32_16x16x32_bf16 v[82:85], v[154:157], v[214:217], v[82:85]
	v_mfma_f32_16x16x32_bf16 v[126:129], v[158:161], v[182:185], v[126:129]
	v_mfma_f32_16x16x32_bf16 v[126:129], v[162:165], v[186:189], v[126:129]
	v_mfma_f32_16x16x32_bf16 v[110:113], v[158:161], v[190:193], v[110:113]
	v_mfma_f32_16x16x32_bf16 v[110:113], v[162:165], v[198:201], v[110:113]
	v_mfma_f32_16x16x32_bf16 v[94:97], v[158:161], v[202:205], v[94:97]
	v_mfma_f32_16x16x32_bf16 v[94:97], v[162:165], v[206:209], v[94:97]
	v_mfma_f32_16x16x32_bf16 v[78:81], v[158:161], v[210:213], v[78:81]
	v_mfma_f32_16x16x32_bf16 v[78:81], v[162:165], v[214:217], v[78:81]
	v_mfma_f32_16x16x32_bf16 v[122:125], v[166:169], v[182:185], v[122:125]
	v_mfma_f32_16x16x32_bf16 v[122:125], v[170:173], v[186:189], v[122:125]
	v_mfma_f32_16x16x32_bf16 v[106:109], v[166:169], v[190:193], v[106:109]
	v_mfma_f32_16x16x32_bf16 v[106:109], v[170:173], v[198:201], v[106:109]
	v_mfma_f32_16x16x32_bf16 v[90:93], v[166:169], v[202:205], v[90:93]
	v_mfma_f32_16x16x32_bf16 v[90:93], v[170:173], v[206:209], v[90:93]
	v_mfma_f32_16x16x32_bf16 v[74:77], v[166:169], v[210:213], v[74:77]
	v_mfma_f32_16x16x32_bf16 v[74:77], v[170:173], v[214:217], v[74:77]
	v_mfma_f32_16x16x32_bf16 v[118:121], v[174:177], v[182:185], v[118:121]
	v_mfma_f32_16x16x32_bf16 v[118:121], v[178:181], v[186:189], v[118:121]
	v_mfma_f32_16x16x32_bf16 v[102:105], v[174:177], v[190:193], v[102:105]
	v_mfma_f32_16x16x32_bf16 v[102:105], v[178:181], v[198:201], v[102:105]
	v_mfma_f32_16x16x32_bf16 v[86:89], v[174:177], v[202:205], v[86:89]
	v_mfma_f32_16x16x32_bf16 v[86:89], v[178:181], v[206:209], v[86:89]
	v_mfma_f32_16x16x32_bf16 v[70:73], v[174:177], v[210:213], v[70:73]
	v_mfma_f32_16x16x32_bf16 v[70:73], v[178:181], v[214:217], v[70:73]
	s_barrier
	s_add_i32 s14, s46, s19
	v_lshl_add_u64 v[148:149], v[148:149], 0, s[28:29]
	s_mov_b32 m0, s14
	ds_read_b128 v[182:185], v152 offset:49152
	ds_read_b128 v[186:189], v152 offset:50176
	ds_read_b128 v[190:193], v152 offset:51200
	ds_read_b128 v[198:201], v152 offset:52224
	ds_read_b128 v[202:205], v152 offset:53248
	ds_read_b128 v[206:209], v152 offset:54272
	ds_read_b128 v[210:213], v152 offset:55296
	ds_read_b128 v[214:217], v152 offset:56320
	global_load_lds_dwordx4 v[148:149], off
	s_add_i32 m0, s14, 0x2000
	s_add_u32 s12, s12, 0x40080
	v_lshl_add_u64 v[148:149], v[218:219], 0, s[28:29]
	s_addc_u32 s13, s13, 0
	s_add_i32 s14, s47, s19
	global_load_lds_dwordx4 v[148:149], off
	v_lshl_add_u64 v[148:149], s[12:13], 0, v[134:135]
	s_mov_b32 m0, s14
	s_nop 0
	global_load_lds_dwordx4 v[148:149], off
	v_lshl_add_u64 v[148:149], s[12:13], 0, v[138:139]
	s_add_i32 m0, s14, 0x2000
	s_nop 0
	global_load_lds_dwordx4 v[148:149], off
	v_lshl_add_u64 v[148:149], v[220:221], 0, s[28:29]
	s_mov_b32 m0, s30
	s_nop 0
	global_load_lds_dwordx4 v[148:149], off
	v_lshl_add_u64 v[148:149], v[222:223], 0, s[28:29]
	s_mov_b32 m0, s31
	s_nop 0
	global_load_lds_dwordx4 v[148:149], off
	s_waitcnt vmcnt(8)
	s_waitcnt lgkmcnt(0)
	s_cmp_lg_u32 s45, 12
	s_cbranch_scc1 .Lrs_in_skip
	v_lshl_add_u32 v148, s38, 8, v5
	v_ashrrev_i32_e32 v149, 31, v148
	v_lshl_add_u64 v[148:149], v[148:149], 2, s[6:7]
	global_load_dword v226, v[148:149], off
	global_load_dword v227, v[148:149], off offset:64
	global_load_dword v228, v[148:149], off offset:128
	global_load_dword v229, v[148:149], off offset:192
	global_load_dword v238, v[148:149], off offset:512
	global_load_dword v239, v[148:149], off offset:576
	global_load_dword v240, v[148:149], off offset:640
	global_load_dword v241, v[148:149], off offset:704
; #define PG8_STAGE(bufoff, gbase, voff) do { _Pragma("unroll") for (int _i = 0; _i < 2; ++_i) \
;         __builtin_amdgcn_global_load_lds((const unsigned*)((const char*)(gbase) + (voff)[_i]), (PG8_LAS unsigned*)(lds + (bufoff) + ldsw + _i * 8192), 16, 0, 0); } while (0)
; #define PG8_LDA(dst, b, h) do { _Pragma("unroll") for (int m = 0; m < 4; ++m) _Pragma("unroll") for (int k = 0; k < 2; ++k) dst[m][k] = *(const PG8_LAS bf16x8*)(lds + PG8_SA(b, h) + aoff + m * 2048 + k * 1024); } while (0)
; #define PG8_MMA(ai, bj, At, Bt) do { __builtin_amdgcn_s_setprio(1); _Pragma("unroll") for (int m = 0; m < 4; ++m) _Pragma("unroll") for (int n = 0; n < 2; ++n) _Pragma("unroll") for (int k = 0; k < 2; ++k) \
;         acc[ai][bj][m][n] = __builtin_amdgcn_mfma_f32_16x16x32_bf16(Bt[n][k], At[m][k], acc[ai][bj][m][n], 0, 0, 0); __builtin_amdgcn_s_setprio(0); } while (0)
; #define PG8_WAIT_V(n) asm volatile("s_waitcnt vmcnt(" #n ")" ::: "memory")
; #define PG8_WAIT_L(n) asm volatile("s_waitcnt lgkmcnt(" #n ")" ::: "memory")
; #define PG8_BAR __builtin_amdgcn_s_barrier()
; #define PG8_SCHED __builtin_amdgcn_sched_barrier(0)
; template <class Epi, class Sched, bool ALIGN_EPI = false, bool SP2 = false>
; __device__ __forceinline__ void gemm_phase(PG8_LAS unsigned char* lds, const Gemm g, const Sched& S, const Epi& E, const int tid_in) {
;     ...
;         for (int t = 0; t < nt; t += 2) {
;             const bool last = (t == nt - 2);
;             const char* a1 = cA + (size_t)(t + 1) * kstep;
;             const char* a2 = last ? nA : cA + (size_t)(t + 2) * kstep; const char* b2 = last ? nB : cB + (size_t)(t + 2) * kstep;
;             const char* a3 = a2 + kstep; const char* b3 = b2 + kstep;
;     ...
;             PG8_WAIT_V(8); PG8_WAIT_L(0); PG8_BAR; PG8_MMA(0, 0, At, B0); PG8_MMA(0, 1, At, B1); PG8_BAR; PG8_SCHED;
;             PG8_LDA(At, 1, 1); PG8_STAGE(PG8_SB(1, 0), b3, voffB); PG8_STAGE(PG8_SB(1, 1), b3 + hstep, voffB); PG8_STAGE(PG8_SA(1, 0), a3, voffA);
;             PG8_WAIT_V(8); PG8_WAIT_L(0); PG8_BAR; PG8_MMA(1, 0, At, B0); PG8_MMA(1, 1, At, B1); PG8_BAR; PG8_SCHED;
.Lrs_in_skip:
	s_barrier
	v_mfma_f32_16x16x32_bf16 v[66:69], v[246:249], v[182:185], v[66:69]
	v_mfma_f32_16x16x32_bf16 v[66:69], v[154:157], v[186:189], v[66:69]
	v_mfma_f32_16x16x32_bf16 v[50:53], v[246:249], v[190:193], v[50:53]
	v_mfma_f32_16x16x32_bf16 v[50:53], v[154:157], v[198:201], v[50:53]
	v_mfma_f32_16x16x32_bf16 v[34:37], v[246:249], v[202:205], v[34:37]
	v_mfma_f32_16x16x32_bf16 v[34:37], v[154:157], v[206:209], v[34:37]
	v_mfma_f32_16x16x32_bf16 v[18:21], v[246:249], v[210:213], v[18:21]
	v_mfma_f32_16x16x32_bf16 v[18:21], v[154:157], v[214:217], v[18:21]
	v_mfma_f32_16x16x32_bf16 v[62:65], v[158:161], v[182:185], v[62:65]
	v_mfma_f32_16x16x32_bf16 v[62:65], v[162:165], v[186:189], v[62:65]
	v_mfma_f32_16x16x32_bf16 v[46:49], v[158:161], v[190:193], v[46:49]
	v_mfma_f32_16x16x32_bf16 v[46:49], v[162:165], v[198:201], v[46:49]
	v_mfma_f32_16x16x32_bf16 v[30:33], v[158:161], v[202:205], v[30:33]
	v_mfma_f32_16x16x32_bf16 v[30:33], v[162:165], v[206:209], v[30:33]
	v_mfma_f32_16x16x32_bf16 v[14:17], v[158:161], v[210:213], v[14:17]
	v_mfma_f32_16x16x32_bf16 v[14:17], v[162:165], v[214:217], v[14:17]
	v_mfma_f32_16x16x32_bf16 v[58:61], v[166:169], v[182:185], v[58:61]
	v_mfma_f32_16x16x32_bf16 v[58:61], v[170:173], v[186:189], v[58:61]
	v_mfma_f32_16x16x32_bf16 v[42:45], v[166:169], v[190:193], v[42:45]
	v_mfma_f32_16x16x32_bf16 v[42:45], v[170:173], v[198:201], v[42:45]
	v_mfma_f32_16x16x32_bf16 v[26:29], v[166:169], v[202:205], v[26:29]
	v_mfma_f32_16x16x32_bf16 v[26:29], v[170:173], v[206:209], v[26:29]
	v_mfma_f32_16x16x32_bf16 v[10:13], v[166:169], v[210:213], v[10:13]
	v_mfma_f32_16x16x32_bf16 v[10:13], v[170:173], v[214:217], v[10:13]
	v_mfma_f32_16x16x32_bf16 v[54:57], v[174:177], v[182:185], v[54:57]
	v_mfma_f32_16x16x32_bf16 v[54:57], v[178:181], v[186:189], v[54:57]
	v_mfma_f32_16x16x32_bf16 v[38:41], v[174:177], v[190:193], v[38:41]
	v_mfma_f32_16x16x32_bf16 v[38:41], v[178:181], v[198:201], v[38:41]
	v_mfma_f32_16x16x32_bf16 v[22:25], v[174:177], v[202:205], v[22:25]
	v_mfma_f32_16x16x32_bf16 v[22:25], v[178:181], v[206:209], v[22:25]
	v_mfma_f32_16x16x32_bf16 v[6:9], v[174:177], v[210:213], v[6:9]
	v_mfma_f32_16x16x32_bf16 v[6:9], v[178:181], v[214:217], v[6:9]
	s_barrier
	s_add_i32 s45, s45, 2
	s_add_u32 s42, s42, 0x100
	s_addc_u32 s43, s43, 0
	s_add_u32 s25, s25, 0x100
	s_addc_u32 s39, s39, 0
	s_cmp_gt_u32 s45, 13
	s_cbranch_scc0 .LBB0_93
	s_and_b64 vcc, exec, s[8:9]
	s_cbranch_vccz .LBB0_96
	s_barrier
